# mixer phase order split by blockIdx bit 4 (pairs of ranks) instead of bit 3
# speedup vs baseline: 1.0104x; 1.0104x over previous
; #define LAS __attribute__((address_space(3)))
; #define LAUNDER() int tp = TID0(); const int tid = tp, lane = tp & 63, wave = __builtin_amdgcn_readfirstlane(tp >> 6); (void)tid; (void)lane; (void)wave
; __global__ void __launch_bounds__(512) fwd_kernel(Args a) {
;     ...
;         if (IN(pb + 2)) {
;             if (EN_B) { LAUNDER(); LAS char* vt = (LAS char*)lds + wave * 16384;
;                 (void)vt; for (int u = blockIdx.x; u < 256; u += G) { mixerB2_unit(u, l, PROJ, YC, a.in[6] + l * 128, a.in[7] + l * 64, KMAX + l * 1024, (LAS char*)lds, tid, wave, lane); } __syncthreads(); }
;             if (EN_S1) { LAUNDER(); __syncthreads();
;                 for (int u = blockIdx.x; u < 256; u += G) ssd_part1_unit(u, PROJ, DT, H, WDT + l * 16384, a.in[11] + l * 8, a.in[8] + l * 5 * 768, a.in[9] + l * 768, a.in[10] + l * 8, STATES, TOT, lds, tid, wave, lane);
;                 __syncthreads(); }
;             if (EN_A) { LAUNDER(); LAS char* vt = (LAS char*)lds + wave * 16384;
;                 for (int u = blockIdx.x; u < 512; u += G) { mixerA1_unit(u, PROJ, YC, LPA, KMAX + l * 1024, vt, wave, lane); } }
;             if (EN_D) { LAUNDER(); LAS char* vt = (LAS char*)lds + wave * 16384;
;                 int hcur = -1; float rmax = 0.f;
;                 for (int u = blockIdx.x; u < 512; u += G) { const int hd = (u >> 4) & 3; if (hd != hcur) { rmax = d_stage_rpb(a.in[14] + l * 4 * 15 * 31, hd, vt, lane); hcur = hd; }
;                     mixerD2_unit(u, PROJ, YC, rmax, KMAX + l * 1024, vt, wave, lane); } }
;         }
.Lmx_b:
	s_cmp_eq_u32 s101, 0
	s_cbranch_scc0 .Lmx_b_go
	s_bitcmp1_b32 s66, 4
	s_cbranch_scc0 .Lmx_b_go
	s_mov_b32 s101, 1
	v_readlane_b32 s0, v253, 56
	v_readlane_b32 s1, v253, 57
	s_nop 1
	v_cndmask_b32_e64 v6, 0, 1, s[0:1]
	s_nop 0
	v_cmp_ne_u32_e64 s[36:37], 1, v6
	s_branch .LBB0_262
